# SSD scan unit rewritten as 4-wave chunked f32-MFMA (v_mfma_f32_16x16x4_f32) in both layers; no LDS broadcast reads
# speedup vs baseline: 1.0275x; 1.0151x over previous
.LBB0_354:
	s_ashr_i32 s60, s33, 5
	s_and_b64 s[0:1], s[2:3], exec
	s_cselect_b32 s0, 8, 0
	s_add_i32 s60, s60, s0
	s_bfe_u32 s26, s33, 0x30002
	s_and_b32 s61, s33, 3
	s_mul_i32 s24, s60, 0x1010
	s_lshl_b32 s0, s60, 6
	s_add_i32 s0, s0, 0x7e80
	s_add_i32 s4, s60, -8
	s_cmp_lt_i32 s60, 8
	s_cselect_b64 s[8:9], -1, 0
	s_cselect_b32 s59, 0x1010, 64
	s_cselect_b32 s24, s24, s0
	s_cselect_b32 s6, s60, s4
	s_mov_b32 s7, 0
	v_readfirstlane_b32 s82, v148
	s_lshr_b32 s82, s82, 6
	v_and_b32_e32 v0, 15, v148
	v_bfe_u32 v1, v148, 4, 2
	v_mul_u32_u24_e32 v40, 0x2a00, v0
	v_lshl_add_u32 v80, v1, 3, v40
	v_lshlrev_b32_e32 v41, 2, v1
	v_mov_b32_e32 v121, 0
	v_mov_b32_e32 v122, 0xf149f2ca
	v_add_u32_e32 v40, 0, v41
	v_cmp_le_u32_e32 vcc, v40, v0
	s_nop 1
	v_cndmask_b32_e32 v92, v122, v121, vcc
	v_lshlrev_b32_e32 v88, 2, v40
	v_mul_u32_u24_e32 v40, 0x2a00, v40
	v_lshl_add_u32 v81, v0, 1, v40
	v_add_u32_e32 v40, 1, v41
	v_cmp_le_u32_e32 vcc, v40, v0
	s_nop 1
	v_cndmask_b32_e32 v93, v122, v121, vcc
	v_lshlrev_b32_e32 v89, 2, v40
	v_mul_u32_u24_e32 v40, 0x2a00, v40
	v_lshl_add_u32 v82, v0, 1, v40
	v_add_u32_e32 v40, 2, v41
	v_cmp_le_u32_e32 vcc, v40, v0
	s_nop 1
	v_cndmask_b32_e32 v94, v122, v121, vcc
	v_lshlrev_b32_e32 v90, 2, v40
	v_mul_u32_u24_e32 v40, 0x2a00, v40
	v_lshl_add_u32 v83, v0, 1, v40
	v_add_u32_e32 v40, 3, v41
	v_cmp_le_u32_e32 vcc, v40, v0
	s_nop 1
	v_cndmask_b32_e32 v95, v122, v121, vcc
	v_lshlrev_b32_e32 v91, 2, v40
	v_mul_u32_u24_e32 v40, 0x2a00, v40
	v_lshl_add_u32 v84, v0, 1, v40
	v_lshlrev_b32_e32 v85, 5, v0
	v_bfe_u32 v40, v148, 2, 4
	v_mul_u32_u24_e32 v40, 0x2a00, v40
	v_and_b32_e32 v41, 3, v148
	v_lshl_add_u32 v86, v41, 7, v40
	v_lshl_add_u32 v40, s61, 4, v0
	v_lshlrev_b32_e32 v40, 9, v40
	v_lshl_add_u32 v87, v1, 4, v40
	v_lshl_add_u32 v87, s82, 7, v87
	v_and_b32_e32 v40, 63, v148
	v_lshlrev_b32_e32 v124, 4, v40
	v_lshl_add_u32 v123, s82, 10, v124
	v_mov_b32_e32 v4, 0
	v_mov_b32_e32 v5, 0
	v_mov_b32_e32 v6, 0
	v_mov_b32_e32 v7, 0
	v_mov_b32_e32 v8, 0
	v_mov_b32_e32 v9, 0
	v_mov_b32_e32 v10, 0
	v_mov_b32_e32 v11, 0
	v_mov_b32_e32 v12, 0
	v_mov_b32_e32 v13, 0
	v_mov_b32_e32 v14, 0
	v_mov_b32_e32 v15, 0
	v_mov_b32_e32 v16, 0
	v_mov_b32_e32 v17, 0
	v_mov_b32_e32 v18, 0
	v_mov_b32_e32 v19, 0
	v_mov_b32_e32 v20, 0
	v_mov_b32_e32 v21, 0
	v_mov_b32_e32 v22, 0
	v_mov_b32_e32 v23, 0
	v_mov_b32_e32 v24, 0
	v_mov_b32_e32 v25, 0
	v_mov_b32_e32 v26, 0
	v_mov_b32_e32 v27, 0
	v_mov_b32_e32 v28, 0
	v_mov_b32_e32 v29, 0
	v_mov_b32_e32 v30, 0
	v_mov_b32_e32 v31, 0
	v_mov_b32_e32 v32, 0
	v_mov_b32_e32 v33, 0
	v_mov_b32_e32 v34, 0
	v_mov_b32_e32 v35, 0
	v_mov_b32_e32 v48, 0
	v_mov_b32_e32 v49, 0
	v_mov_b32_e32 v50, 0
	v_mov_b32_e32 v51, 0
	v_mov_b32_e32 v52, 0
	v_mov_b32_e32 v53, 0
	v_mov_b32_e32 v54, 0
	v_mov_b32_e32 v55, 0
	v_mov_b32_e32 v56, 0
	v_mov_b32_e32 v57, 0
	v_mov_b32_e32 v58, 0
	v_mov_b32_e32 v59, 0
	v_mov_b32_e32 v64, 0
	v_mov_b32_e32 v65, 0
	v_mov_b32_e32 v66, 0
	v_mov_b32_e32 v67, 0
	v_mov_b32_e32 v68, 0
	v_mov_b32_e32 v69, 0
	v_mov_b32_e32 v70, 0
	v_mov_b32_e32 v71, 0
	v_mov_b32_e32 v72, 0
	v_mov_b32_e32 v73, 0
	v_mov_b32_e32 v74, 0
	v_mov_b32_e32 v75, 0
	v_mov_b32_e32 v76, 0
	v_mov_b32_e32 v77, 0
	v_mov_b32_e32 v78, 0
	v_mov_b32_e32 v79, 0
	s_mul_i32 s0, s24, 0x2a00
	s_add_u32 s4, s46, s0
	s_addc_u32 s5, s47, 0
	s_lshl_b32 s0, s26, 7
	s_lshl_b32 s1, s61, 5
	s_add_i32 s0, s0, s1
	s_add_u32 s28, s4, s0
	s_addc_u32 s29, s5, 0
	s_lshr_b32 s0, s26, 2
	s_lshl_b32 s0, s0, 8
	s_addk_i32 s0, 0x1000
	s_add_u32 s78, s4, s0
	s_addc_u32 s79, s5, 0
	s_lshl_b32 s0, s82, 6
	s_add_u32 s30, s78, s0
	s_addc_u32 s31, s79, 0
	s_mov_b64 s[4:5], s[78:79]
	s_lshl_b32 s0, s24, 5
	s_lshl_b32 s1, s26, 2
	s_add_i32 s0, s0, s1
	s_add_u32 s62, s20, s0
	s_addc_u32 s63, s21, 0
	s_lshr_b32 s81, s59, 4
	s_mov_b32 s80, 0
	s_mov_b64 s[64:65], s[4:5]
	s_or_b32 s0, s26, s52
	s_lshl_b32 s0, s0, 2
	v_readlane_b32 s4, v159, 12
	v_readlane_b32 s5, v159, 13
	s_add_u32 s4, s4, s0
	s_addc_u32 s5, s5, 0
	s_load_dword s12, s[4:5], 0x0
	s_waitcnt lgkmcnt(0)
	v_readlane_b32 s4, v159, 14
	v_readlane_b32 s5, v159, 15
	s_add_u32 s4, s4, s0
	s_addc_u32 s5, s5, 0
	s_load_dword s25, s[4:5], 0x0
	s_waitcnt lgkmcnt(0)
	v_readlane_b32 s4, v159, 16
	v_readlane_b32 s5, v159, 17
	s_add_u32 s4, s4, s0
	s_addc_u32 s5, s5, 0
	s_load_dword s27, s[4:5], 0x0
	s_waitcnt lgkmcnt(0)
	v_mov_b32_e32 v40, s25
	v_mul_f32_e32 v40, 0x3fb8aa3b, v40
	v_exp_f32_e32 v40, v40
	s_nop 0
	v_mul_f32_e32 v40, 0xbfb8aa3b, v40
	s_nop 0
	v_readfirstlane_b32 s25, v40
	s_cmp_lt_i32 s60, 8
	s_cbranch_scc1 .Lssd0_nostate
	s_lshl_b64 s[0:1], s[6:7], 3
	s_add_u32 s0, s0, s16
	s_addc_u32 s1, s1, s17
	s_add_u32 s0, s0, s26
	s_addc_u32 s1, s1, 0
	s_lshl_b64 s[0:1], s[0:1], 15
	v_readlane_b32 s4, v158, 1
	v_readlane_b32 s5, v158, 2
	s_add_u32 s0, s0, s4
	s_addc_u32 s1, s1, s5
	global_load_dwordx4 v[72:75], v87, s[0:1] offset:0
	global_load_dwordx4 v[76:79], v87, s[0:1] offset:64
.Lssd0_nostate:
	s_add_i32 s0, s81, -1
	s_add_i32 s83, s80, 1
	s_min_i32 s83, s83, s0
	s_add_i32 s93, s80, 2
	s_min_i32 s93, s93, s0
	s_add_i32 s95, s80, 3
	s_min_i32 s95, s95, s0
	s_lshl_b32 s0, s93, 9
	s_add_u32 s76, s62, s0
	s_addc_u32 s77, s63, 0
	s_mul_i32 s0, s80, 0x2a000
	s_add_u32 s66, s28, s0
	s_addc_u32 s67, s29, 0
	s_mul_i32 s0, s83, 0x2a000
	s_add_u32 s68, s28, s0
	s_addc_u32 s69, s29, 0
	s_add_u32 s72, s30, s0
	s_addc_u32 s73, s31, 0
	s_mul_i32 s0, s93, 0x2a000
	s_add_u32 s70, s28, s0
	s_addc_u32 s71, s29, 0
	s_add_u32 s74, s30, s0
	s_addc_u32 s75, s31, 0
	s_mul_i32 s0, s95, 0x2a000
	s_add_u32 s78, s64, s0
	s_addc_u32 s79, s65, 0
	global_load_short_d16_hi v20, v80, s[30:31] offset:512
	global_load_short_d16_hi v4, v80, s[30:31] offset:0
	global_load_short_d16_hi v21, v80, s[30:31] offset:514
	global_load_short_d16_hi v5, v80, s[30:31] offset:2
	global_load_short_d16_hi v22, v80, s[30:31] offset:516
	global_load_short_d16_hi v6, v80, s[30:31] offset:4
	global_load_short_d16_hi v23, v80, s[30:31] offset:518
	global_load_short_d16_hi v7, v80, s[30:31] offset:6
	global_load_short_d16_hi v24, v80, s[30:31] offset:544
	global_load_short_d16_hi v8, v80, s[30:31] offset:32
	global_load_short_d16_hi v25, v80, s[30:31] offset:546
	global_load_short_d16_hi v9, v80, s[30:31] offset:34
	global_load_short_d16_hi v26, v80, s[30:31] offset:548
	global_load_short_d16_hi v10, v80, s[30:31] offset:36
	global_load_short_d16_hi v27, v80, s[30:31] offset:550
	global_load_short_d16_hi v11, v80, s[30:31] offset:38
	global_load_short_d16_hi v48, v81, s[28:29] offset:3072
	global_load_short_d16_hi v49, v82, s[28:29] offset:3072
	global_load_short_d16_hi v50, v83, s[28:29] offset:3072
	global_load_short_d16_hi v51, v84, s[28:29] offset:3072
	global_load_dword v60, v85, s[62:63]
	global_load_short_d16_hi v56, v81, s[28:29]
	global_load_short_d16_hi v57, v82, s[28:29]
	global_load_short_d16_hi v58, v83, s[28:29]
	global_load_short_d16_hi v59, v84, s[28:29]
	s_lshl_b32 s0, s83, 9
	s_add_u32 s0, s62, s0
	s_addc_u32 s1, s63, 0
	global_load_short_d16_hi v28, v80, s[72:73] offset:512
	global_load_short_d16_hi v12, v80, s[72:73] offset:0
	global_load_short_d16_hi v29, v80, s[72:73] offset:514
	global_load_short_d16_hi v13, v80, s[72:73] offset:2
	global_load_short_d16_hi v30, v80, s[72:73] offset:516
	global_load_short_d16_hi v14, v80, s[72:73] offset:4
	global_load_short_d16_hi v31, v80, s[72:73] offset:518
	global_load_short_d16_hi v15, v80, s[72:73] offset:6
	global_load_short_d16_hi v32, v80, s[72:73] offset:544
	global_load_short_d16_hi v16, v80, s[72:73] offset:32
	global_load_short_d16_hi v33, v80, s[72:73] offset:546
	global_load_short_d16_hi v17, v80, s[72:73] offset:34
	global_load_short_d16_hi v34, v80, s[72:73] offset:548
	global_load_short_d16_hi v18, v80, s[72:73] offset:36
	global_load_short_d16_hi v35, v80, s[72:73] offset:550
	global_load_short_d16_hi v19, v80, s[72:73] offset:38
	global_load_short_d16_hi v52, v81, s[68:69] offset:3072
	global_load_short_d16_hi v53, v82, s[68:69] offset:3072
	global_load_short_d16_hi v54, v83, s[68:69] offset:3072
	global_load_short_d16_hi v55, v84, s[68:69] offset:3072
	global_load_dword v61, v85, s[0:1]
	global_load_short_d16_hi v64, v81, s[30:31] offset:0
	global_load_short_d16_hi v65, v81, s[30:31] offset:32
	global_load_short_d16_hi v66, v82, s[30:31] offset:0
	global_load_short_d16_hi v67, v82, s[30:31] offset:32
	global_load_short_d16_hi v68, v83, s[30:31] offset:0
	global_load_short_d16_hi v69, v83, s[30:31] offset:32
	global_load_short_d16_hi v70, v84, s[30:31] offset:0
	global_load_short_d16_hi v71, v84, s[30:31] offset:32
	s_waitcnt vmcnt(0)
.Lssd0_loop:
.Lssd0_blk0:
	s_nop 15
	s_add_i32 s0, s81, -1
	s_add_i32 s83, s80, 1
	s_min_i32 s83, s83, s0
	s_add_i32 s93, s80, 2
	s_min_i32 s93, s93, s0
	s_add_i32 s95, s80, 3
	s_min_i32 s95, s95, s0
	s_lshl_b32 s0, s93, 9
	s_add_u32 s76, s62, s0
	s_addc_u32 s77, s63, 0
	s_mul_i32 s0, s80, 0x2a000
	s_add_u32 s66, s28, s0
	s_addc_u32 s67, s29, 0
	s_mul_i32 s0, s83, 0x2a000
	s_add_u32 s68, s28, s0
	s_addc_u32 s69, s29, 0
	s_add_u32 s72, s30, s0
	s_addc_u32 s73, s31, 0
	s_mul_i32 s0, s93, 0x2a000
	s_add_u32 s70, s28, s0
	s_addc_u32 s71, s29, 0
	s_add_u32 s74, s30, s0
	s_addc_u32 s75, s31, 0
	s_mul_i32 s0, s95, 0x2a000
	s_add_u32 s78, s64, s0
	s_addc_u32 s79, s65, 0
	s_waitcnt vmcnt(37)
	v_add_f32_e32 v40, s12, v60
	v_mul_f32_e32 v41, 0x3fb8aa3b, v40
	v_exp_f32_e32 v41, v41
	s_nop 0
	v_add_f32_e32 v41, 1.0, v41
	v_log_f32_e32 v41, v41
	s_nop 0
	v_mul_f32_e32 v41, 0x3f317218, v41
	v_cmp_lt_f32_e32 vcc, 0x41a00000, v40
	s_nop 1
	v_cndmask_b32_e32 v122, v41, v40, vcc
	v_mul_f32_e32 v40, s25, v122
	s_nop 1
	v_add_f32_dpp v41, v40, v40 row_shr:1 row_mask:0xf bank_mask:0xf bound_ctrl:1
	s_nop 1
	v_add_f32_dpp v40, v41, v41 row_shr:2 row_mask:0xf bank_mask:0xf bound_ctrl:1
	s_nop 1
	v_add_f32_dpp v41, v40, v40 row_shr:4 row_mask:0xf bank_mask:0xf bound_ctrl:1
	s_nop 1
	v_add_f32_dpp v121, v41, v41 row_shr:8 row_mask:0xf bank_mask:0xf bound_ctrl:1
	s_nop 0
	v_readlane_b32 s32, v121, 15
	ds_bpermute_b32 v96, v88, v121
	ds_bpermute_b32 v97, v89, v121
	ds_bpermute_b32 v98, v90, v121
	ds_bpermute_b32 v99, v91, v121
	ds_bpermute_b32 v104, v88, v122
	ds_bpermute_b32 v105, v89, v122
	ds_bpermute_b32 v106, v90, v122
	ds_bpermute_b32 v107, v91, v122
	v_exp_f32_e32 v120, s32
	s_waitcnt lgkmcnt(0)
	v_sub_f32_e32 v108, s32, v96
	v_mul_f32_e32 v104, v48, v104
	v_sub_f32_e32 v109, s32, v97
	v_mul_f32_e32 v105, v49, v105
	v_sub_f32_e32 v110, s32, v98
	v_mul_f32_e32 v106, v50, v106
	v_sub_f32_e32 v111, s32, v99
	v_mul_f32_e32 v107, v51, v107
	v_exp_f32_e32 v108, v108
	v_exp_f32_e32 v109, v109
	v_exp_f32_e32 v110, v110
	v_exp_f32_e32 v111, v111
	v_mul_f32_e32 v108, v104, v108
	v_mul_f32_e32 v109, v105, v109
	v_mul_f32_e32 v110, v106, v110
	v_mul_f32_e32 v111, v107, v111
	s_waitcnt vmcnt(56)
	v_mfma_f32_16x16x4_f32 v[36:39], v4, v20, 0
	v_mfma_f32_16x16x4_f32 v[44:47], v20, v72, 0
	global_load_short_d16_hi v20, v80, s[74:75] offset:512
	global_load_short_d16_hi v4, v80, s[74:75] offset:0
	s_waitcnt vmcnt(56)
	v_mfma_f32_16x16x4_f32 v[36:39], v5, v21, v[36:39]
	v_mfma_f32_16x16x4_f32 v[44:47], v21, v73, v[44:47]
	global_load_short_d16_hi v21, v80, s[74:75] offset:514
	global_load_short_d16_hi v5, v80, s[74:75] offset:2
	s_waitcnt vmcnt(56)
	v_mfma_f32_16x16x4_f32 v[36:39], v6, v22, v[36:39]
	v_mfma_f32_16x16x4_f32 v[44:47], v22, v74, v[44:47]
	global_load_short_d16_hi v22, v80, s[74:75] offset:516
	global_load_short_d16_hi v6, v80, s[74:75] offset:4
	s_waitcnt vmcnt(56)
	v_mfma_f32_16x16x4_f32 v[36:39], v7, v23, v[36:39]
	v_mfma_f32_16x16x4_f32 v[44:47], v23, v75, v[44:47]
	global_load_short_d16_hi v23, v80, s[74:75] offset:518
	global_load_short_d16_hi v7, v80, s[74:75] offset:6
	s_waitcnt vmcnt(56)
	v_mfma_f32_16x16x4_f32 v[36:39], v8, v24, v[36:39]
	v_mfma_f32_16x16x4_f32 v[44:47], v24, v76, v[44:47]
	global_load_short_d16_hi v24, v80, s[74:75] offset:544
	global_load_short_d16_hi v8, v80, s[74:75] offset:32
	s_waitcnt vmcnt(56)
	v_mfma_f32_16x16x4_f32 v[36:39], v9, v25, v[36:39]
	v_mfma_f32_16x16x4_f32 v[44:47], v25, v77, v[44:47]
	global_load_short_d16_hi v25, v80, s[74:75] offset:546
	global_load_short_d16_hi v9, v80, s[74:75] offset:34
	s_waitcnt vmcnt(56)
	v_mfma_f32_16x16x4_f32 v[36:39], v10, v26, v[36:39]
	v_mfma_f32_16x16x4_f32 v[44:47], v26, v78, v[44:47]
	global_load_short_d16_hi v26, v80, s[74:75] offset:548
	global_load_short_d16_hi v10, v80, s[74:75] offset:36
	s_waitcnt vmcnt(56)
	v_mfma_f32_16x16x4_f32 v[36:39], v11, v27, v[36:39]
	v_mfma_f32_16x16x4_f32 v[44:47], v27, v79, v[44:47]
	global_load_short_d16_hi v27, v80, s[74:75] offset:550
	global_load_short_d16_hi v11, v80, s[74:75] offset:38
	s_cmp_eq_u32 s82, 0
	s_cbranch_scc1 .Lssd0_w0_0
	s_nop 5
	ds_write_b128 v123, v[36:39] offset:0
	ds_write_b128 v123, v[44:47] offset:4096
	s_waitcnt lgkmcnt(0)
	s_barrier
	s_branch .Lssd0_mrg_0
.Lssd0_w0_0:
	s_barrier
	ds_read_b128 v[128:131], v124 offset:1024
	ds_read_b128 v[132:135], v124 offset:5120
	ds_read_b128 v[136:139], v124 offset:2048
	ds_read_b128 v[140:143], v124 offset:6144
	ds_read_b128 v[144:147], v124 offset:3072
	ds_read_b128 v[150:153], v124 offset:7168
	s_waitcnt vmcnt(29)
	v_mul_f32_e32 v116, 0xbfb8aa3b, v56
	v_exp_f32_e32 v116, v116
	v_mul_f32_e32 v112, s27, v48
	v_sub_f32_e32 v100, v121, v96
	v_mul_f32_e32 v117, 0xbfb8aa3b, v57
	v_exp_f32_e32 v117, v117
	v_mul_f32_e32 v113, s27, v49
	v_sub_f32_e32 v101, v121, v97
	v_mul_f32_e32 v118, 0xbfb8aa3b, v58
	v_exp_f32_e32 v118, v118
	v_mul_f32_e32 v114, s27, v50
	v_sub_f32_e32 v102, v121, v98
	v_mul_f32_e32 v119, 0xbfb8aa3b, v59
	v_exp_f32_e32 v119, v119
	v_mul_f32_e32 v115, s27, v51
	v_sub_f32_e32 v103, v121, v99
	v_add_f32_e32 v116, 1.0, v116
	v_min_f32_e32 v100, 0, v100
	v_add_f32_e32 v117, 1.0, v117
	v_min_f32_e32 v101, 0, v101
	v_add_f32_e32 v118, 1.0, v118
	v_min_f32_e32 v102, 0, v102
	v_add_f32_e32 v119, 1.0, v119
	v_min_f32_e32 v103, 0, v103
	v_rcp_f32_e32 v116, v116
	v_add_f32_e32 v100, v92, v100
	v_rcp_f32_e32 v117, v117
	v_add_f32_e32 v101, v93, v101
	v_rcp_f32_e32 v118, v118
	v_add_f32_e32 v102, v94, v102
	v_rcp_f32_e32 v119, v119
	v_add_f32_e32 v103, v95, v103
	v_mul_f32_e32 v116, v116, v56
	v_exp_f32_e32 v100, v100
	v_exp_f32_e32 v96, v96
	v_mul_f32_e32 v117, v117, v57
	v_exp_f32_e32 v101, v101
	v_exp_f32_e32 v97, v97
	v_mul_f32_e32 v118, v118, v58
	v_exp_f32_e32 v102, v102
	v_exp_f32_e32 v98, v98
	v_mul_f32_e32 v119, v119, v59
	v_exp_f32_e32 v103, v103
	v_exp_f32_e32 v99, v99
	s_waitcnt lgkmcnt(0)
	v_add_f32_e32 v36, v36, v128
	v_add_f32_e32 v37, v37, v129
	v_add_f32_e32 v38, v38, v130
	v_add_f32_e32 v39, v39, v131
	v_add_f32_e32 v44, v44, v132
	v_add_f32_e32 v45, v45, v133
	v_add_f32_e32 v46, v46, v134
	v_add_f32_e32 v47, v47, v135
	v_add_f32_e32 v36, v36, v136
	v_add_f32_e32 v37, v37, v137
	v_add_f32_e32 v38, v38, v138
	v_add_f32_e32 v39, v39, v139
	v_add_f32_e32 v44, v44, v140
	v_add_f32_e32 v45, v45, v141
	v_add_f32_e32 v46, v46, v142
	v_add_f32_e32 v47, v47, v143
	v_add_f32_e32 v36, v36, v144
	v_add_f32_e32 v37, v37, v145
	v_add_f32_e32 v38, v38, v146
	v_add_f32_e32 v39, v39, v147
	v_add_f32_e32 v44, v44, v150
	v_add_f32_e32 v45, v45, v151
	v_add_f32_e32 v46, v46, v152
	v_add_f32_e32 v47, v47, v153
	v_mul_f32_e32 v36, v36, v100
	v_mul_f32_e32 v37, v37, v101
	v_mul_f32_e32 v38, v38, v102
	v_mul_f32_e32 v39, v39, v103
	v_mul_f32_e32 v44, v44, v96
	v_mul_f32_e32 v45, v45, v97
	v_mul_f32_e32 v46, v46, v98
	v_mul_f32_e32 v47, v47, v99
	s_nop 0
	s_nop 0
	v_mfma_f32_16x16x4_f32 v[44:47], v36, v104, v[44:47]
	v_mfma_f32_16x16x4_f32 v[44:47], v37, v105, v[44:47]
	v_mfma_f32_16x16x4_f32 v[44:47], v38, v106, v[44:47]
	v_mfma_f32_16x16x4_f32 v[44:47], v39, v107, v[44:47]
	global_load_dword v56, v86, s[78:79]
	global_load_short_d16_hi v56, v81, s[68:69]
	global_load_short_d16_hi v57, v82, s[68:69]
	global_load_short_d16_hi v58, v83, s[68:69]
	global_load_short_d16_hi v59, v84, s[68:69]
	s_nop 5
	v_add_f32_e32 v44, v44, v112
	v_add_f32_e32 v45, v45, v113
	v_add_f32_e32 v46, v46, v114
	v_add_f32_e32 v47, v47, v115
	v_mul_f32_e32 v44, v44, v116
	v_mul_f32_e32 v45, v45, v117
	v_mul_f32_e32 v46, v46, v118
	v_mul_f32_e32 v47, v47, v119
	v_cvt_pk_bf16_f32 v40, v44, v45
	v_cvt_pk_bf16_f32 v41, v46, v47
	global_store_short v81, v40, s[66:67]
	global_store_short_d16_hi v82, v40, s[66:67]
	global_store_short v83, v41, s[66:67]
	global_store_short_d16_hi v84, v41, s[66:67]
.Lssd0_mrg_0:
	s_nop 15
	global_load_short_d16_hi v48, v81, s[70:71] offset:3072
	global_load_short_d16_hi v49, v82, s[70:71] offset:3072
	global_load_short_d16_hi v50, v83, s[70:71] offset:3072
	global_load_short_d16_hi v51, v84, s[70:71] offset:3072
	global_load_dword v60, v85, s[76:77]
	v_mul_f32_e32 v72, v120, v72
	v_mul_f32_e32 v73, v120, v73
	v_mul_f32_e32 v74, v120, v74
	v_mul_f32_e32 v75, v120, v75
	v_mul_f32_e32 v76, v120, v76
	v_mul_f32_e32 v77, v120, v77
	v_mul_f32_e32 v78, v120, v78
	v_mul_f32_e32 v79, v120, v79
	s_waitcnt vmcnt(28)
	v_mfma_f32_16x16x4_f32 v[72:75], v64, v108, v[72:75]
	global_load_short_d16_hi v64, v81, s[72:73] offset:0
	s_waitcnt vmcnt(28)
	v_mfma_f32_16x16x4_f32 v[76:79], v65, v108, v[76:79]
	global_load_short_d16_hi v65, v81, s[72:73] offset:32
	s_waitcnt vmcnt(28)
	v_mfma_f32_16x16x4_f32 v[72:75], v66, v109, v[72:75]
	global_load_short_d16_hi v66, v82, s[72:73] offset:0
	s_waitcnt vmcnt(28)
	v_mfma_f32_16x16x4_f32 v[76:79], v67, v109, v[76:79]
	global_load_short_d16_hi v67, v82, s[72:73] offset:32
	s_waitcnt vmcnt(28)
	v_mfma_f32_16x16x4_f32 v[72:75], v68, v110, v[72:75]
	global_load_short_d16_hi v68, v83, s[72:73] offset:0
	s_waitcnt vmcnt(28)
	v_mfma_f32_16x16x4_f32 v[76:79], v69, v110, v[76:79]
	global_load_short_d16_hi v69, v83, s[72:73] offset:32
	s_waitcnt vmcnt(28)
	v_mfma_f32_16x16x4_f32 v[72:75], v70, v111, v[72:75]
	global_load_short_d16_hi v70, v84, s[72:73] offset:0
	s_waitcnt vmcnt(28)
	v_mfma_f32_16x16x4_f32 v[76:79], v71, v111, v[76:79]
	global_load_short_d16_hi v71, v84, s[72:73] offset:32
	s_add_i32 s80, s80, 1
	s_cmp_lt_i32 s80, s81
	s_cbranch_scc0 .Lssd0_fin
.Lssd0_blk1:
	s_nop 15
	s_add_i32 s0, s81, -1
	s_add_i32 s83, s80, 1
	s_min_i32 s83, s83, s0
	s_add_i32 s93, s80, 2
	s_min_i32 s93, s93, s0
	s_add_i32 s95, s80, 3
	s_min_i32 s95, s95, s0
	s_lshl_b32 s0, s93, 9
	s_add_u32 s76, s62, s0
	s_addc_u32 s77, s63, 0
	s_mul_i32 s0, s80, 0x2a000
	s_add_u32 s66, s28, s0
	s_addc_u32 s67, s29, 0
	s_mul_i32 s0, s83, 0x2a000
	s_add_u32 s68, s28, s0
	s_addc_u32 s69, s29, 0
	s_add_u32 s72, s30, s0
	s_addc_u32 s73, s31, 0
	s_mul_i32 s0, s93, 0x2a000
	s_add_u32 s70, s28, s0
	s_addc_u32 s71, s29, 0
	s_add_u32 s74, s30, s0
	s_addc_u32 s75, s31, 0
	s_mul_i32 s0, s95, 0x2a000
	s_add_u32 s78, s64, s0
	s_addc_u32 s79, s65, 0
	s_waitcnt vmcnt(37)
	v_add_f32_e32 v40, s12, v61
	v_mul_f32_e32 v41, 0x3fb8aa3b, v40
	v_exp_f32_e32 v41, v41
	s_nop 0
	v_add_f32_e32 v41, 1.0, v41
	v_log_f32_e32 v41, v41
	s_nop 0
	v_mul_f32_e32 v41, 0x3f317218, v41
	v_cmp_lt_f32_e32 vcc, 0x41a00000, v40
	s_nop 1
	v_cndmask_b32_e32 v122, v41, v40, vcc
	v_mul_f32_e32 v40, s25, v122
	s_nop 1
	v_add_f32_dpp v41, v40, v40 row_shr:1 row_mask:0xf bank_mask:0xf bound_ctrl:1
	s_nop 1
	v_add_f32_dpp v40, v41, v41 row_shr:2 row_mask:0xf bank_mask:0xf bound_ctrl:1
	s_nop 1
	v_add_f32_dpp v41, v40, v40 row_shr:4 row_mask:0xf bank_mask:0xf bound_ctrl:1
	s_nop 1
	v_add_f32_dpp v121, v41, v41 row_shr:8 row_mask:0xf bank_mask:0xf bound_ctrl:1
	s_nop 0
	v_readlane_b32 s32, v121, 15
	ds_bpermute_b32 v96, v88, v121
	ds_bpermute_b32 v97, v89, v121
	ds_bpermute_b32 v98, v90, v121
	ds_bpermute_b32 v99, v91, v121
	ds_bpermute_b32 v104, v88, v122
	ds_bpermute_b32 v105, v89, v122
	ds_bpermute_b32 v106, v90, v122
	ds_bpermute_b32 v107, v91, v122
	v_exp_f32_e32 v120, s32
	s_waitcnt lgkmcnt(0)
	v_sub_f32_e32 v108, s32, v96
	v_mul_f32_e32 v104, v52, v104
	v_sub_f32_e32 v109, s32, v97
	v_mul_f32_e32 v105, v53, v105
	v_sub_f32_e32 v110, s32, v98
	v_mul_f32_e32 v106, v54, v106
	v_sub_f32_e32 v111, s32, v99
	v_mul_f32_e32 v107, v55, v107
	v_exp_f32_e32 v108, v108
	v_exp_f32_e32 v109, v109
	v_exp_f32_e32 v110, v110
	v_exp_f32_e32 v111, v111
	v_mul_f32_e32 v108, v104, v108
	v_mul_f32_e32 v109, v105, v109
	v_mul_f32_e32 v110, v106, v110
	v_mul_f32_e32 v111, v107, v111
	s_waitcnt vmcnt(56)
	v_mfma_f32_16x16x4_f32 v[36:39], v12, v28, 0
	v_mfma_f32_16x16x4_f32 v[44:47], v28, v72, 0
	global_load_short_d16_hi v28, v80, s[74:75] offset:512
	global_load_short_d16_hi v12, v80, s[74:75] offset:0
	s_waitcnt vmcnt(56)
	v_mfma_f32_16x16x4_f32 v[36:39], v13, v29, v[36:39]
	v_mfma_f32_16x16x4_f32 v[44:47], v29, v73, v[44:47]
	global_load_short_d16_hi v29, v80, s[74:75] offset:514
	global_load_short_d16_hi v13, v80, s[74:75] offset:2
	s_waitcnt vmcnt(56)
	v_mfma_f32_16x16x4_f32 v[36:39], v14, v30, v[36:39]
	v_mfma_f32_16x16x4_f32 v[44:47], v30, v74, v[44:47]
	global_load_short_d16_hi v30, v80, s[74:75] offset:516
	global_load_short_d16_hi v14, v80, s[74:75] offset:4
	s_waitcnt vmcnt(56)
	v_mfma_f32_16x16x4_f32 v[36:39], v15, v31, v[36:39]
	v_mfma_f32_16x16x4_f32 v[44:47], v31, v75, v[44:47]
	global_load_short_d16_hi v31, v80, s[74:75] offset:518
	global_load_short_d16_hi v15, v80, s[74:75] offset:6
	s_waitcnt vmcnt(56)
	v_mfma_f32_16x16x4_f32 v[36:39], v16, v32, v[36:39]
	v_mfma_f32_16x16x4_f32 v[44:47], v32, v76, v[44:47]
	global_load_short_d16_hi v32, v80, s[74:75] offset:544
	global_load_short_d16_hi v16, v80, s[74:75] offset:32
	s_waitcnt vmcnt(56)
	v_mfma_f32_16x16x4_f32 v[36:39], v17, v33, v[36:39]
	v_mfma_f32_16x16x4_f32 v[44:47], v33, v77, v[44:47]
	global_load_short_d16_hi v33, v80, s[74:75] offset:546
	global_load_short_d16_hi v17, v80, s[74:75] offset:34
	s_waitcnt vmcnt(56)
	v_mfma_f32_16x16x4_f32 v[36:39], v18, v34, v[36:39]
	v_mfma_f32_16x16x4_f32 v[44:47], v34, v78, v[44:47]
	global_load_short_d16_hi v34, v80, s[74:75] offset:548
	global_load_short_d16_hi v18, v80, s[74:75] offset:36
	s_waitcnt vmcnt(56)
	v_mfma_f32_16x16x4_f32 v[36:39], v19, v35, v[36:39]
	v_mfma_f32_16x16x4_f32 v[44:47], v35, v79, v[44:47]
	global_load_short_d16_hi v35, v80, s[74:75] offset:550
	global_load_short_d16_hi v19, v80, s[74:75] offset:38
	s_cmp_eq_u32 s82, 0
	s_cbranch_scc1 .Lssd0_w0_1
	s_nop 5
	ds_write_b128 v123, v[36:39] offset:8192
	ds_write_b128 v123, v[44:47] offset:12288
	s_waitcnt lgkmcnt(0)
	s_barrier
	s_branch .Lssd0_mrg_1
.Lssd0_w0_1:
	s_barrier
	ds_read_b128 v[128:131], v124 offset:9216
	ds_read_b128 v[132:135], v124 offset:13312
	ds_read_b128 v[136:139], v124 offset:10240
	ds_read_b128 v[140:143], v124 offset:14336
	ds_read_b128 v[144:147], v124 offset:11264
	ds_read_b128 v[150:153], v124 offset:15360
	s_waitcnt vmcnt(29)
	v_mul_f32_e32 v116, 0xbfb8aa3b, v56
	v_exp_f32_e32 v116, v116
	v_mul_f32_e32 v112, s27, v52
	v_sub_f32_e32 v100, v121, v96
	v_mul_f32_e32 v117, 0xbfb8aa3b, v57
	v_exp_f32_e32 v117, v117
	v_mul_f32_e32 v113, s27, v53
	v_sub_f32_e32 v101, v121, v97
	v_mul_f32_e32 v118, 0xbfb8aa3b, v58
	v_exp_f32_e32 v118, v118
	v_mul_f32_e32 v114, s27, v54
	v_sub_f32_e32 v102, v121, v98
	v_mul_f32_e32 v119, 0xbfb8aa3b, v59
	v_exp_f32_e32 v119, v119
	v_mul_f32_e32 v115, s27, v55
	v_sub_f32_e32 v103, v121, v99
	v_add_f32_e32 v116, 1.0, v116
	v_min_f32_e32 v100, 0, v100
	v_add_f32_e32 v117, 1.0, v117
	v_min_f32_e32 v101, 0, v101
	v_add_f32_e32 v118, 1.0, v118
	v_min_f32_e32 v102, 0, v102
	v_add_f32_e32 v119, 1.0, v119
	v_min_f32_e32 v103, 0, v103
	v_rcp_f32_e32 v116, v116
	v_add_f32_e32 v100, v92, v100
	v_rcp_f32_e32 v117, v117
	v_add_f32_e32 v101, v93, v101
	v_rcp_f32_e32 v118, v118
	v_add_f32_e32 v102, v94, v102
	v_rcp_f32_e32 v119, v119
	v_add_f32_e32 v103, v95, v103
	v_mul_f32_e32 v116, v116, v56
	v_exp_f32_e32 v100, v100
	v_exp_f32_e32 v96, v96
	v_mul_f32_e32 v117, v117, v57
	v_exp_f32_e32 v101, v101
	v_exp_f32_e32 v97, v97
	v_mul_f32_e32 v118, v118, v58
	v_exp_f32_e32 v102, v102
	v_exp_f32_e32 v98, v98
	v_mul_f32_e32 v119, v119, v59
	v_exp_f32_e32 v103, v103
	v_exp_f32_e32 v99, v99
	s_waitcnt lgkmcnt(0)
	v_add_f32_e32 v36, v36, v128
	v_add_f32_e32 v37, v37, v129
	v_add_f32_e32 v38, v38, v130
	v_add_f32_e32 v39, v39, v131
	v_add_f32_e32 v44, v44, v132
	v_add_f32_e32 v45, v45, v133
	v_add_f32_e32 v46, v46, v134
	v_add_f32_e32 v47, v47, v135
	v_add_f32_e32 v36, v36, v136
	v_add_f32_e32 v37, v37, v137
	v_add_f32_e32 v38, v38, v138
	v_add_f32_e32 v39, v39, v139
	v_add_f32_e32 v44, v44, v140
	v_add_f32_e32 v45, v45, v141
	v_add_f32_e32 v46, v46, v142
	v_add_f32_e32 v47, v47, v143
	v_add_f32_e32 v36, v36, v144
	v_add_f32_e32 v37, v37, v145
	v_add_f32_e32 v38, v38, v146
	v_add_f32_e32 v39, v39, v147
	v_add_f32_e32 v44, v44, v150
	v_add_f32_e32 v45, v45, v151
	v_add_f32_e32 v46, v46, v152
	v_add_f32_e32 v47, v47, v153
	v_mul_f32_e32 v36, v36, v100
	v_mul_f32_e32 v37, v37, v101
	v_mul_f32_e32 v38, v38, v102
	v_mul_f32_e32 v39, v39, v103
	v_mul_f32_e32 v44, v44, v96
	v_mul_f32_e32 v45, v45, v97
	v_mul_f32_e32 v46, v46, v98
	v_mul_f32_e32 v47, v47, v99
	s_nop 0
	s_nop 0
	v_mfma_f32_16x16x4_f32 v[44:47], v36, v104, v[44:47]
	v_mfma_f32_16x16x4_f32 v[44:47], v37, v105, v[44:47]
	v_mfma_f32_16x16x4_f32 v[44:47], v38, v106, v[44:47]
	v_mfma_f32_16x16x4_f32 v[44:47], v39, v107, v[44:47]
	global_load_dword v56, v86, s[78:79]
	global_load_short_d16_hi v56, v81, s[68:69]
	global_load_short_d16_hi v57, v82, s[68:69]
	global_load_short_d16_hi v58, v83, s[68:69]
	global_load_short_d16_hi v59, v84, s[68:69]
	s_nop 5
	v_add_f32_e32 v44, v44, v112
	v_add_f32_e32 v45, v45, v113
	v_add_f32_e32 v46, v46, v114
	v_add_f32_e32 v47, v47, v115
	v_mul_f32_e32 v44, v44, v116
	v_mul_f32_e32 v45, v45, v117
	v_mul_f32_e32 v46, v46, v118
	v_mul_f32_e32 v47, v47, v119
	v_cvt_pk_bf16_f32 v40, v44, v45
	v_cvt_pk_bf16_f32 v41, v46, v47
	global_store_short v81, v40, s[66:67]
	global_store_short_d16_hi v82, v40, s[66:67]
	global_store_short v83, v41, s[66:67]
	global_store_short_d16_hi v84, v41, s[66:67]
.Lssd0_mrg_1:
	s_nop 15
	global_load_short_d16_hi v52, v81, s[70:71] offset:3072
	global_load_short_d16_hi v53, v82, s[70:71] offset:3072
	global_load_short_d16_hi v54, v83, s[70:71] offset:3072
	global_load_short_d16_hi v55, v84, s[70:71] offset:3072
	global_load_dword v61, v85, s[76:77]
	v_mul_f32_e32 v72, v120, v72
	v_mul_f32_e32 v73, v120, v73
	v_mul_f32_e32 v74, v120, v74
	v_mul_f32_e32 v75, v120, v75
	v_mul_f32_e32 v76, v120, v76
	v_mul_f32_e32 v77, v120, v77
	v_mul_f32_e32 v78, v120, v78
	v_mul_f32_e32 v79, v120, v79
	s_waitcnt vmcnt(28)
	v_mfma_f32_16x16x4_f32 v[72:75], v64, v108, v[72:75]
	global_load_short_d16_hi v64, v81, s[72:73] offset:0
	s_waitcnt vmcnt(28)
	v_mfma_f32_16x16x4_f32 v[76:79], v65, v108, v[76:79]
	global_load_short_d16_hi v65, v81, s[72:73] offset:32
	s_waitcnt vmcnt(28)
	v_mfma_f32_16x16x4_f32 v[72:75], v66, v109, v[72:75]
	global_load_short_d16_hi v66, v82, s[72:73] offset:0
	s_waitcnt vmcnt(28)
	v_mfma_f32_16x16x4_f32 v[76:79], v67, v109, v[76:79]
	global_load_short_d16_hi v67, v82, s[72:73] offset:32
	s_waitcnt vmcnt(28)
	v_mfma_f32_16x16x4_f32 v[72:75], v68, v110, v[72:75]
	global_load_short_d16_hi v68, v83, s[72:73] offset:0
	s_waitcnt vmcnt(28)
	v_mfma_f32_16x16x4_f32 v[76:79], v69, v110, v[76:79]
	global_load_short_d16_hi v69, v83, s[72:73] offset:32
	s_waitcnt vmcnt(28)
	v_mfma_f32_16x16x4_f32 v[72:75], v70, v111, v[72:75]
	global_load_short_d16_hi v70, v84, s[72:73] offset:0
	s_waitcnt vmcnt(28)
	v_mfma_f32_16x16x4_f32 v[76:79], v71, v111, v[76:79]
	global_load_short_d16_hi v71, v84, s[72:73] offset:32
	s_add_i32 s80, s80, 1
	s_cmp_lt_i32 s80, s81
	s_cbranch_scc1 .Lssd0_loop
.Lssd0_fin:
	s_waitcnt vmcnt(0)
	s_nop 15
	s_lshl_b64 s[0:1], s[6:7], 3
	s_add_u32 s0, s0, s16
	s_addc_u32 s1, s1, s17
	s_add_u32 s0, s0, s26
	s_addc_u32 s1, s1, 0
	s_lshl_b64 s[0:1], s[0:1], 15
	s_add_u32 s0, s42, s0
	s_addc_u32 s1, s43, s1
	s_cmp_lt_i32 s60, 8
	s_mov_b32 s4, 0x8200000
	s_cselect_b32 s4, s4, 0x8c4c000
	s_add_u32 s0, s0, s4
	s_addc_u32 s1, s1, 0
	global_store_dwordx4 v87, v[72:75], s[0:1] offset:0
	global_store_dwordx4 v87, v[76:79], s[0:1] offset:64
	s_waitcnt vmcnt(0)
	v_mov_b32_e32 v20, v148
	s_or_b32 s0, s26, s61
	s_cmp_eq_u32 s0, 0
	s_barrier
	s_cbranch_scc1 .LBB0_372
	s_branch .LBB0_316

.LBB0_1057:
	s_ashr_i32 s54, s33, 5
	s_and_b64 s[0:1], s[2:3], exec
	s_cselect_b32 s0, 8, 0
	s_add_i32 s54, s54, s0
	s_bfe_u32 s26, s33, 0x30002
	s_and_b32 s56, s33, 3
	s_mul_i32 s24, s54, 0x1010
	s_lshl_b32 s0, s54, 6
	s_add_i32 s0, s0, 0x7e80
	s_add_i32 s4, s54, -8
	s_cmp_lt_i32 s54, 8
	s_cselect_b64 s[8:9], -1, 0
	s_cselect_b32 s53, 0x1010, 64
	s_cselect_b32 s24, s24, s0
	s_cselect_b32 s10, s54, s4
	s_mov_b32 s11, 0
	v_readfirstlane_b32 s77, v148
	s_lshr_b32 s77, s77, 6
	v_and_b32_e32 v0, 15, v148
	v_bfe_u32 v1, v148, 4, 2
	v_mul_u32_u24_e32 v40, 0x2a00, v0
	v_lshl_add_u32 v80, v1, 3, v40
	v_lshlrev_b32_e32 v41, 2, v1
	v_mov_b32_e32 v121, 0
	v_mov_b32_e32 v122, 0xf149f2ca
	v_add_u32_e32 v40, 0, v41
	v_cmp_le_u32_e32 vcc, v40, v0
	s_nop 1
	v_cndmask_b32_e32 v92, v122, v121, vcc
	v_lshlrev_b32_e32 v88, 2, v40
	v_mul_u32_u24_e32 v40, 0x2a00, v40
	v_lshl_add_u32 v81, v0, 1, v40
	v_add_u32_e32 v40, 1, v41
	v_cmp_le_u32_e32 vcc, v40, v0
	s_nop 1
	v_cndmask_b32_e32 v93, v122, v121, vcc
	v_lshlrev_b32_e32 v89, 2, v40
	v_mul_u32_u24_e32 v40, 0x2a00, v40
	v_lshl_add_u32 v82, v0, 1, v40
	v_add_u32_e32 v40, 2, v41
	v_cmp_le_u32_e32 vcc, v40, v0
	s_nop 1
	v_cndmask_b32_e32 v94, v122, v121, vcc
	v_lshlrev_b32_e32 v90, 2, v40
	v_mul_u32_u24_e32 v40, 0x2a00, v40
	v_lshl_add_u32 v83, v0, 1, v40
	v_add_u32_e32 v40, 3, v41
	v_cmp_le_u32_e32 vcc, v40, v0
	s_nop 1
	v_cndmask_b32_e32 v95, v122, v121, vcc
	v_lshlrev_b32_e32 v91, 2, v40
	v_mul_u32_u24_e32 v40, 0x2a00, v40
	v_lshl_add_u32 v84, v0, 1, v40
	v_lshlrev_b32_e32 v85, 5, v0
	v_bfe_u32 v40, v148, 2, 4
	v_mul_u32_u24_e32 v40, 0x2a00, v40
	v_and_b32_e32 v41, 3, v148
	v_lshl_add_u32 v86, v41, 7, v40
	v_lshl_add_u32 v40, s56, 4, v0
	v_lshlrev_b32_e32 v40, 9, v40
	v_lshl_add_u32 v87, v1, 4, v40
	v_lshl_add_u32 v87, s77, 7, v87
	v_and_b32_e32 v40, 63, v148
	v_lshlrev_b32_e32 v124, 4, v40
	v_lshl_add_u32 v123, s77, 10, v124
	v_mov_b32_e32 v4, 0
	v_mov_b32_e32 v5, 0
	v_mov_b32_e32 v6, 0
	v_mov_b32_e32 v7, 0
	v_mov_b32_e32 v8, 0
	v_mov_b32_e32 v9, 0
	v_mov_b32_e32 v10, 0
	v_mov_b32_e32 v11, 0
	v_mov_b32_e32 v12, 0
	v_mov_b32_e32 v13, 0
	v_mov_b32_e32 v14, 0
	v_mov_b32_e32 v15, 0
	v_mov_b32_e32 v16, 0
	v_mov_b32_e32 v17, 0
	v_mov_b32_e32 v18, 0
	v_mov_b32_e32 v19, 0
	v_mov_b32_e32 v20, 0
	v_mov_b32_e32 v21, 0
	v_mov_b32_e32 v22, 0
	v_mov_b32_e32 v23, 0
	v_mov_b32_e32 v24, 0
	v_mov_b32_e32 v25, 0
	v_mov_b32_e32 v26, 0
	v_mov_b32_e32 v27, 0
	v_mov_b32_e32 v28, 0
	v_mov_b32_e32 v29, 0
	v_mov_b32_e32 v30, 0
	v_mov_b32_e32 v31, 0
	v_mov_b32_e32 v32, 0
	v_mov_b32_e32 v33, 0
	v_mov_b32_e32 v34, 0
	v_mov_b32_e32 v35, 0
	v_mov_b32_e32 v48, 0
	v_mov_b32_e32 v49, 0
	v_mov_b32_e32 v50, 0
	v_mov_b32_e32 v51, 0
	v_mov_b32_e32 v52, 0
	v_mov_b32_e32 v53, 0
	v_mov_b32_e32 v54, 0
	v_mov_b32_e32 v55, 0
	v_mov_b32_e32 v56, 0
	v_mov_b32_e32 v57, 0
	v_mov_b32_e32 v58, 0
	v_mov_b32_e32 v59, 0
	v_mov_b32_e32 v64, 0
	v_mov_b32_e32 v65, 0
	v_mov_b32_e32 v66, 0
	v_mov_b32_e32 v67, 0
	v_mov_b32_e32 v68, 0
	v_mov_b32_e32 v69, 0
	v_mov_b32_e32 v70, 0
	v_mov_b32_e32 v71, 0
	v_mov_b32_e32 v72, 0
	v_mov_b32_e32 v73, 0
	v_mov_b32_e32 v74, 0
	v_mov_b32_e32 v75, 0
	v_mov_b32_e32 v76, 0
	v_mov_b32_e32 v77, 0
	v_mov_b32_e32 v78, 0
	v_mov_b32_e32 v79, 0
	s_mul_i32 s0, s24, 0x2a00
	s_add_u32 s4, s46, s0
	s_addc_u32 s5, s47, 0
	s_lshl_b32 s0, s26, 7
	s_lshl_b32 s1, s56, 5
	s_add_i32 s0, s0, s1
	s_add_u32 s28, s4, s0
	s_addc_u32 s29, s5, 0
	s_lshr_b32 s0, s26, 2
	s_lshl_b32 s0, s0, 8
	s_addk_i32 s0, 0x1000
	s_add_u32 s74, s4, s0
	s_addc_u32 s75, s5, 0
	s_lshl_b32 s0, s77, 6
	s_add_u32 s30, s74, s0
	s_addc_u32 s31, s75, 0
	s_mov_b64 s[4:5], s[74:75]
	s_lshl_b32 s0, s24, 5
	s_lshl_b32 s1, s26, 2
	s_add_i32 s0, s0, s1
	s_add_u32 s58, s20, s0
	s_addc_u32 s59, s21, 0
	s_lshr_b32 s76, s53, 4
	s_mov_b32 s57, 0
	s_mov_b64 s[60:61], s[4:5]
	s_or_b32 s0, s26, s36
	s_lshl_b32 s0, s0, 2
	v_readlane_b32 s4, v159, 12
	v_readlane_b32 s5, v159, 13
	s_add_u32 s4, s4, s0
	s_addc_u32 s5, s5, 0
	s_load_dword s14, s[4:5], 0x0
	s_waitcnt lgkmcnt(0)
	v_readlane_b32 s4, v159, 14
	v_readlane_b32 s5, v159, 15
	s_add_u32 s4, s4, s0
	s_addc_u32 s5, s5, 0
	s_load_dword s25, s[4:5], 0x0
	s_waitcnt lgkmcnt(0)
	v_readlane_b32 s4, v159, 16
	v_readlane_b32 s5, v159, 17
	s_add_u32 s4, s4, s0
	s_addc_u32 s5, s5, 0
	s_load_dword s27, s[4:5], 0x0
	s_waitcnt lgkmcnt(0)
	v_mov_b32_e32 v40, s25
	v_mul_f32_e32 v40, 0x3fb8aa3b, v40
	v_exp_f32_e32 v40, v40
	s_nop 0
	v_mul_f32_e32 v40, 0xbfb8aa3b, v40
	s_nop 0
	v_readfirstlane_b32 s25, v40
	s_cmp_lt_i32 s54, 8
	s_cbranch_scc1 .Lssd1_nostate
	s_lshl_b64 s[0:1], s[10:11], 3
	s_add_u32 s0, s0, s16
	s_addc_u32 s1, s1, s17
	s_add_u32 s0, s0, s26
	s_addc_u32 s1, s1, 0
	s_lshl_b64 s[0:1], s[0:1], 15
	v_readlane_b32 s4, v158, 1
	v_readlane_b32 s5, v158, 2
	s_add_u32 s0, s0, s4
	s_addc_u32 s1, s1, s5
	global_load_dwordx4 v[72:75], v87, s[0:1] offset:0
	global_load_dwordx4 v[76:79], v87, s[0:1] offset:64
.Lssd1_nostate:
	s_add_i32 s0, s76, -1
	s_add_i32 s78, s57, 1
	s_min_i32 s78, s78, s0
	s_add_i32 s79, s57, 2
	s_min_i32 s79, s79, s0
	s_add_i32 s80, s57, 3
	s_min_i32 s80, s80, s0
	s_lshl_b32 s0, s79, 9
	s_add_u32 s72, s58, s0
	s_addc_u32 s73, s59, 0
	s_mul_i32 s0, s57, 0x2a000
	s_add_u32 s62, s28, s0
	s_addc_u32 s63, s29, 0
	s_mul_i32 s0, s78, 0x2a000
	s_add_u32 s64, s28, s0
	s_addc_u32 s65, s29, 0
	s_add_u32 s68, s30, s0
	s_addc_u32 s69, s31, 0
	s_mul_i32 s0, s79, 0x2a000
	s_add_u32 s66, s28, s0
	s_addc_u32 s67, s29, 0
	s_add_u32 s70, s30, s0
	s_addc_u32 s71, s31, 0
	s_mul_i32 s0, s80, 0x2a000
	s_add_u32 s74, s60, s0
	s_addc_u32 s75, s61, 0
	global_load_short_d16_hi v20, v80, s[30:31] offset:512
	global_load_short_d16_hi v4, v80, s[30:31] offset:0
	global_load_short_d16_hi v21, v80, s[30:31] offset:514
	global_load_short_d16_hi v5, v80, s[30:31] offset:2
	global_load_short_d16_hi v22, v80, s[30:31] offset:516
	global_load_short_d16_hi v6, v80, s[30:31] offset:4
	global_load_short_d16_hi v23, v80, s[30:31] offset:518
	global_load_short_d16_hi v7, v80, s[30:31] offset:6
	global_load_short_d16_hi v24, v80, s[30:31] offset:544
	global_load_short_d16_hi v8, v80, s[30:31] offset:32
	global_load_short_d16_hi v25, v80, s[30:31] offset:546
	global_load_short_d16_hi v9, v80, s[30:31] offset:34
	global_load_short_d16_hi v26, v80, s[30:31] offset:548
	global_load_short_d16_hi v10, v80, s[30:31] offset:36
	global_load_short_d16_hi v27, v80, s[30:31] offset:550
	global_load_short_d16_hi v11, v80, s[30:31] offset:38
	global_load_short_d16_hi v48, v81, s[28:29] offset:3072
	global_load_short_d16_hi v49, v82, s[28:29] offset:3072
	global_load_short_d16_hi v50, v83, s[28:29] offset:3072
	global_load_short_d16_hi v51, v84, s[28:29] offset:3072
	global_load_dword v60, v85, s[58:59]
	global_load_short_d16_hi v56, v81, s[28:29]
	global_load_short_d16_hi v57, v82, s[28:29]
	global_load_short_d16_hi v58, v83, s[28:29]
	global_load_short_d16_hi v59, v84, s[28:29]
	s_lshl_b32 s0, s78, 9
	s_add_u32 s0, s58, s0
	s_addc_u32 s1, s59, 0
	global_load_short_d16_hi v28, v80, s[68:69] offset:512
	global_load_short_d16_hi v12, v80, s[68:69] offset:0
	global_load_short_d16_hi v29, v80, s[68:69] offset:514
	global_load_short_d16_hi v13, v80, s[68:69] offset:2
	global_load_short_d16_hi v30, v80, s[68:69] offset:516
	global_load_short_d16_hi v14, v80, s[68:69] offset:4
	global_load_short_d16_hi v31, v80, s[68:69] offset:518
	global_load_short_d16_hi v15, v80, s[68:69] offset:6
	global_load_short_d16_hi v32, v80, s[68:69] offset:544
	global_load_short_d16_hi v16, v80, s[68:69] offset:32
	global_load_short_d16_hi v33, v80, s[68:69] offset:546
	global_load_short_d16_hi v17, v80, s[68:69] offset:34
	global_load_short_d16_hi v34, v80, s[68:69] offset:548
	global_load_short_d16_hi v18, v80, s[68:69] offset:36
	global_load_short_d16_hi v35, v80, s[68:69] offset:550
	global_load_short_d16_hi v19, v80, s[68:69] offset:38
	global_load_short_d16_hi v52, v81, s[64:65] offset:3072
	global_load_short_d16_hi v53, v82, s[64:65] offset:3072
	global_load_short_d16_hi v54, v83, s[64:65] offset:3072
	global_load_short_d16_hi v55, v84, s[64:65] offset:3072
	global_load_dword v61, v85, s[0:1]
	global_load_short_d16_hi v64, v81, s[30:31] offset:0
	global_load_short_d16_hi v65, v81, s[30:31] offset:32
	global_load_short_d16_hi v66, v82, s[30:31] offset:0
	global_load_short_d16_hi v67, v82, s[30:31] offset:32
	global_load_short_d16_hi v68, v83, s[30:31] offset:0
	global_load_short_d16_hi v69, v83, s[30:31] offset:32
	global_load_short_d16_hi v70, v84, s[30:31] offset:0
	global_load_short_d16_hi v71, v84, s[30:31] offset:32
	s_waitcnt vmcnt(0)
.Lssd1_loop:
.Lssd1_blk0:
	s_nop 15
	s_add_i32 s0, s76, -1
	s_add_i32 s78, s57, 1
	s_min_i32 s78, s78, s0
	s_add_i32 s79, s57, 2
	s_min_i32 s79, s79, s0
	s_add_i32 s80, s57, 3
	s_min_i32 s80, s80, s0
	s_lshl_b32 s0, s79, 9
	s_add_u32 s72, s58, s0
	s_addc_u32 s73, s59, 0
	s_mul_i32 s0, s57, 0x2a000
	s_add_u32 s62, s28, s0
	s_addc_u32 s63, s29, 0
	s_mul_i32 s0, s78, 0x2a000
	s_add_u32 s64, s28, s0
	s_addc_u32 s65, s29, 0
	s_add_u32 s68, s30, s0
	s_addc_u32 s69, s31, 0
	s_mul_i32 s0, s79, 0x2a000
	s_add_u32 s66, s28, s0
	s_addc_u32 s67, s29, 0
	s_add_u32 s70, s30, s0
	s_addc_u32 s71, s31, 0
	s_mul_i32 s0, s80, 0x2a000
	s_add_u32 s74, s60, s0
	s_addc_u32 s75, s61, 0
	s_waitcnt vmcnt(37)
	v_add_f32_e32 v40, s14, v60
	v_mul_f32_e32 v41, 0x3fb8aa3b, v40
	v_exp_f32_e32 v41, v41
	s_nop 0
	v_add_f32_e32 v41, 1.0, v41
	v_log_f32_e32 v41, v41
	s_nop 0
	v_mul_f32_e32 v41, 0x3f317218, v41
	v_cmp_lt_f32_e32 vcc, 0x41a00000, v40
	s_nop 1
	v_cndmask_b32_e32 v122, v41, v40, vcc
	v_mul_f32_e32 v40, s25, v122
	s_nop 1
	v_add_f32_dpp v41, v40, v40 row_shr:1 row_mask:0xf bank_mask:0xf bound_ctrl:1
	s_nop 1
	v_add_f32_dpp v40, v41, v41 row_shr:2 row_mask:0xf bank_mask:0xf bound_ctrl:1
	s_nop 1
	v_add_f32_dpp v41, v40, v40 row_shr:4 row_mask:0xf bank_mask:0xf bound_ctrl:1
	s_nop 1
	v_add_f32_dpp v121, v41, v41 row_shr:8 row_mask:0xf bank_mask:0xf bound_ctrl:1
	s_nop 0
	v_readlane_b32 s32, v121, 15
	ds_bpermute_b32 v96, v88, v121
	ds_bpermute_b32 v97, v89, v121
	ds_bpermute_b32 v98, v90, v121
	ds_bpermute_b32 v99, v91, v121
	ds_bpermute_b32 v104, v88, v122
	ds_bpermute_b32 v105, v89, v122
	ds_bpermute_b32 v106, v90, v122
	ds_bpermute_b32 v107, v91, v122
	v_exp_f32_e32 v120, s32
	s_waitcnt lgkmcnt(0)
	v_sub_f32_e32 v108, s32, v96
	v_mul_f32_e32 v104, v48, v104
	v_sub_f32_e32 v109, s32, v97
	v_mul_f32_e32 v105, v49, v105
	v_sub_f32_e32 v110, s32, v98
	v_mul_f32_e32 v106, v50, v106
	v_sub_f32_e32 v111, s32, v99
	v_mul_f32_e32 v107, v51, v107
	v_exp_f32_e32 v108, v108
	v_exp_f32_e32 v109, v109
	v_exp_f32_e32 v110, v110
	v_exp_f32_e32 v111, v111
	v_mul_f32_e32 v108, v104, v108
	v_mul_f32_e32 v109, v105, v109
	v_mul_f32_e32 v110, v106, v110
	v_mul_f32_e32 v111, v107, v111
	s_waitcnt vmcnt(56)
	v_mfma_f32_16x16x4_f32 v[36:39], v4, v20, 0
	v_mfma_f32_16x16x4_f32 v[44:47], v20, v72, 0
	global_load_short_d16_hi v20, v80, s[70:71] offset:512
	global_load_short_d16_hi v4, v80, s[70:71] offset:0
	s_waitcnt vmcnt(56)
	v_mfma_f32_16x16x4_f32 v[36:39], v5, v21, v[36:39]
	v_mfma_f32_16x16x4_f32 v[44:47], v21, v73, v[44:47]
	global_load_short_d16_hi v21, v80, s[70:71] offset:514
	global_load_short_d16_hi v5, v80, s[70:71] offset:2
	s_waitcnt vmcnt(56)
	v_mfma_f32_16x16x4_f32 v[36:39], v6, v22, v[36:39]
	v_mfma_f32_16x16x4_f32 v[44:47], v22, v74, v[44:47]
	global_load_short_d16_hi v22, v80, s[70:71] offset:516
	global_load_short_d16_hi v6, v80, s[70:71] offset:4
	s_waitcnt vmcnt(56)
	v_mfma_f32_16x16x4_f32 v[36:39], v7, v23, v[36:39]
	v_mfma_f32_16x16x4_f32 v[44:47], v23, v75, v[44:47]
	global_load_short_d16_hi v23, v80, s[70:71] offset:518
	global_load_short_d16_hi v7, v80, s[70:71] offset:6
	s_waitcnt vmcnt(56)
	v_mfma_f32_16x16x4_f32 v[36:39], v8, v24, v[36:39]
	v_mfma_f32_16x16x4_f32 v[44:47], v24, v76, v[44:47]
	global_load_short_d16_hi v24, v80, s[70:71] offset:544
	global_load_short_d16_hi v8, v80, s[70:71] offset:32
	s_waitcnt vmcnt(56)
	v_mfma_f32_16x16x4_f32 v[36:39], v9, v25, v[36:39]
	v_mfma_f32_16x16x4_f32 v[44:47], v25, v77, v[44:47]
	global_load_short_d16_hi v25, v80, s[70:71] offset:546
	global_load_short_d16_hi v9, v80, s[70:71] offset:34
	s_waitcnt vmcnt(56)
	v_mfma_f32_16x16x4_f32 v[36:39], v10, v26, v[36:39]
	v_mfma_f32_16x16x4_f32 v[44:47], v26, v78, v[44:47]
	global_load_short_d16_hi v26, v80, s[70:71] offset:548
	global_load_short_d16_hi v10, v80, s[70:71] offset:36
	s_waitcnt vmcnt(56)
	v_mfma_f32_16x16x4_f32 v[36:39], v11, v27, v[36:39]
	v_mfma_f32_16x16x4_f32 v[44:47], v27, v79, v[44:47]
	global_load_short_d16_hi v27, v80, s[70:71] offset:550
	global_load_short_d16_hi v11, v80, s[70:71] offset:38
	s_cmp_eq_u32 s77, 0
	s_cbranch_scc1 .Lssd1_w0_0
	s_nop 5
	ds_write_b128 v123, v[36:39] offset:0
	ds_write_b128 v123, v[44:47] offset:4096
	s_waitcnt lgkmcnt(0)
	s_barrier
	s_branch .Lssd1_mrg_0
.Lssd1_w0_0:
	s_barrier
	ds_read_b128 v[128:131], v124 offset:1024
	ds_read_b128 v[132:135], v124 offset:5120
	ds_read_b128 v[136:139], v124 offset:2048
	ds_read_b128 v[140:143], v124 offset:6144
	ds_read_b128 v[144:147], v124 offset:3072
	ds_read_b128 v[150:153], v124 offset:7168
	s_waitcnt vmcnt(29)
	v_mul_f32_e32 v116, 0xbfb8aa3b, v56
	v_exp_f32_e32 v116, v116
	v_mul_f32_e32 v112, s27, v48
	v_sub_f32_e32 v100, v121, v96
	v_mul_f32_e32 v117, 0xbfb8aa3b, v57
	v_exp_f32_e32 v117, v117
	v_mul_f32_e32 v113, s27, v49
	v_sub_f32_e32 v101, v121, v97
	v_mul_f32_e32 v118, 0xbfb8aa3b, v58
	v_exp_f32_e32 v118, v118
	v_mul_f32_e32 v114, s27, v50
	v_sub_f32_e32 v102, v121, v98
	v_mul_f32_e32 v119, 0xbfb8aa3b, v59
	v_exp_f32_e32 v119, v119
	v_mul_f32_e32 v115, s27, v51
	v_sub_f32_e32 v103, v121, v99
	v_add_f32_e32 v116, 1.0, v116
	v_min_f32_e32 v100, 0, v100
	v_add_f32_e32 v117, 1.0, v117
	v_min_f32_e32 v101, 0, v101
	v_add_f32_e32 v118, 1.0, v118
	v_min_f32_e32 v102, 0, v102
	v_add_f32_e32 v119, 1.0, v119
	v_min_f32_e32 v103, 0, v103
	v_rcp_f32_e32 v116, v116
	v_add_f32_e32 v100, v92, v100
	v_rcp_f32_e32 v117, v117
	v_add_f32_e32 v101, v93, v101
	v_rcp_f32_e32 v118, v118
	v_add_f32_e32 v102, v94, v102
	v_rcp_f32_e32 v119, v119
	v_add_f32_e32 v103, v95, v103
	v_mul_f32_e32 v116, v116, v56
	v_exp_f32_e32 v100, v100
	v_exp_f32_e32 v96, v96
	v_mul_f32_e32 v117, v117, v57
	v_exp_f32_e32 v101, v101
	v_exp_f32_e32 v97, v97
	v_mul_f32_e32 v118, v118, v58
	v_exp_f32_e32 v102, v102
	v_exp_f32_e32 v98, v98
	v_mul_f32_e32 v119, v119, v59
	v_exp_f32_e32 v103, v103
	v_exp_f32_e32 v99, v99
	s_waitcnt lgkmcnt(0)
	v_add_f32_e32 v36, v36, v128
	v_add_f32_e32 v37, v37, v129
	v_add_f32_e32 v38, v38, v130
	v_add_f32_e32 v39, v39, v131
	v_add_f32_e32 v44, v44, v132
	v_add_f32_e32 v45, v45, v133
	v_add_f32_e32 v46, v46, v134
	v_add_f32_e32 v47, v47, v135
	v_add_f32_e32 v36, v36, v136
	v_add_f32_e32 v37, v37, v137
	v_add_f32_e32 v38, v38, v138
	v_add_f32_e32 v39, v39, v139
	v_add_f32_e32 v44, v44, v140
	v_add_f32_e32 v45, v45, v141
	v_add_f32_e32 v46, v46, v142
	v_add_f32_e32 v47, v47, v143
	v_add_f32_e32 v36, v36, v144
	v_add_f32_e32 v37, v37, v145
	v_add_f32_e32 v38, v38, v146
	v_add_f32_e32 v39, v39, v147
	v_add_f32_e32 v44, v44, v150
	v_add_f32_e32 v45, v45, v151
	v_add_f32_e32 v46, v46, v152
	v_add_f32_e32 v47, v47, v153
	v_mul_f32_e32 v36, v36, v100
	v_mul_f32_e32 v37, v37, v101
	v_mul_f32_e32 v38, v38, v102
	v_mul_f32_e32 v39, v39, v103
	v_mul_f32_e32 v44, v44, v96
	v_mul_f32_e32 v45, v45, v97
	v_mul_f32_e32 v46, v46, v98
	v_mul_f32_e32 v47, v47, v99
	s_nop 0
	s_nop 0
	v_mfma_f32_16x16x4_f32 v[44:47], v36, v104, v[44:47]
	v_mfma_f32_16x16x4_f32 v[44:47], v37, v105, v[44:47]
	v_mfma_f32_16x16x4_f32 v[44:47], v38, v106, v[44:47]
	v_mfma_f32_16x16x4_f32 v[44:47], v39, v107, v[44:47]
	global_load_dword v56, v86, s[74:75]
	global_load_short_d16_hi v56, v81, s[64:65]
	global_load_short_d16_hi v57, v82, s[64:65]
	global_load_short_d16_hi v58, v83, s[64:65]
	global_load_short_d16_hi v59, v84, s[64:65]
	s_nop 5
	v_add_f32_e32 v44, v44, v112
	v_add_f32_e32 v45, v45, v113
	v_add_f32_e32 v46, v46, v114
	v_add_f32_e32 v47, v47, v115
	v_mul_f32_e32 v44, v44, v116
	v_mul_f32_e32 v45, v45, v117
	v_mul_f32_e32 v46, v46, v118
	v_mul_f32_e32 v47, v47, v119
	v_cvt_pk_bf16_f32 v40, v44, v45
	v_cvt_pk_bf16_f32 v41, v46, v47
	global_store_short v81, v40, s[62:63]
	global_store_short_d16_hi v82, v40, s[62:63]
	global_store_short v83, v41, s[62:63]
	global_store_short_d16_hi v84, v41, s[62:63]
.Lssd1_mrg_0:
	s_nop 15
	global_load_short_d16_hi v48, v81, s[66:67] offset:3072
	global_load_short_d16_hi v49, v82, s[66:67] offset:3072
	global_load_short_d16_hi v50, v83, s[66:67] offset:3072
	global_load_short_d16_hi v51, v84, s[66:67] offset:3072
	global_load_dword v60, v85, s[72:73]
	v_mul_f32_e32 v72, v120, v72
	v_mul_f32_e32 v73, v120, v73
	v_mul_f32_e32 v74, v120, v74
	v_mul_f32_e32 v75, v120, v75
	v_mul_f32_e32 v76, v120, v76
	v_mul_f32_e32 v77, v120, v77
	v_mul_f32_e32 v78, v120, v78
	v_mul_f32_e32 v79, v120, v79
	s_waitcnt vmcnt(28)
	v_mfma_f32_16x16x4_f32 v[72:75], v64, v108, v[72:75]
	global_load_short_d16_hi v64, v81, s[68:69] offset:0
	s_waitcnt vmcnt(28)
	v_mfma_f32_16x16x4_f32 v[76:79], v65, v108, v[76:79]
	global_load_short_d16_hi v65, v81, s[68:69] offset:32
	s_waitcnt vmcnt(28)
	v_mfma_f32_16x16x4_f32 v[72:75], v66, v109, v[72:75]
	global_load_short_d16_hi v66, v82, s[68:69] offset:0
	s_waitcnt vmcnt(28)
	v_mfma_f32_16x16x4_f32 v[76:79], v67, v109, v[76:79]
	global_load_short_d16_hi v67, v82, s[68:69] offset:32
	s_waitcnt vmcnt(28)
	v_mfma_f32_16x16x4_f32 v[72:75], v68, v110, v[72:75]
	global_load_short_d16_hi v68, v83, s[68:69] offset:0
	s_waitcnt vmcnt(28)
	v_mfma_f32_16x16x4_f32 v[76:79], v69, v110, v[76:79]
	global_load_short_d16_hi v69, v83, s[68:69] offset:32
	s_waitcnt vmcnt(28)
	v_mfma_f32_16x16x4_f32 v[72:75], v70, v111, v[72:75]
	global_load_short_d16_hi v70, v84, s[68:69] offset:0
	s_waitcnt vmcnt(28)
	v_mfma_f32_16x16x4_f32 v[76:79], v71, v111, v[76:79]
	global_load_short_d16_hi v71, v84, s[68:69] offset:32
	s_add_i32 s57, s57, 1
	s_cmp_lt_i32 s57, s76
	s_cbranch_scc0 .Lssd1_fin
.Lssd1_blk1:
	s_nop 15
	s_add_i32 s0, s76, -1
	s_add_i32 s78, s57, 1
	s_min_i32 s78, s78, s0
	s_add_i32 s79, s57, 2
	s_min_i32 s79, s79, s0
	s_add_i32 s80, s57, 3
	s_min_i32 s80, s80, s0
	s_lshl_b32 s0, s79, 9
	s_add_u32 s72, s58, s0
	s_addc_u32 s73, s59, 0
	s_mul_i32 s0, s57, 0x2a000
	s_add_u32 s62, s28, s0
	s_addc_u32 s63, s29, 0
	s_mul_i32 s0, s78, 0x2a000
	s_add_u32 s64, s28, s0
	s_addc_u32 s65, s29, 0
	s_add_u32 s68, s30, s0
	s_addc_u32 s69, s31, 0
	s_mul_i32 s0, s79, 0x2a000
	s_add_u32 s66, s28, s0
	s_addc_u32 s67, s29, 0
	s_add_u32 s70, s30, s0
	s_addc_u32 s71, s31, 0
	s_mul_i32 s0, s80, 0x2a000
	s_add_u32 s74, s60, s0
	s_addc_u32 s75, s61, 0
	s_waitcnt vmcnt(37)
	v_add_f32_e32 v40, s14, v61
	v_mul_f32_e32 v41, 0x3fb8aa3b, v40
	v_exp_f32_e32 v41, v41
	s_nop 0
	v_add_f32_e32 v41, 1.0, v41
	v_log_f32_e32 v41, v41
	s_nop 0
	v_mul_f32_e32 v41, 0x3f317218, v41
	v_cmp_lt_f32_e32 vcc, 0x41a00000, v40
	s_nop 1
	v_cndmask_b32_e32 v122, v41, v40, vcc
	v_mul_f32_e32 v40, s25, v122
	s_nop 1
	v_add_f32_dpp v41, v40, v40 row_shr:1 row_mask:0xf bank_mask:0xf bound_ctrl:1
	s_nop 1
	v_add_f32_dpp v40, v41, v41 row_shr:2 row_mask:0xf bank_mask:0xf bound_ctrl:1
	s_nop 1
	v_add_f32_dpp v41, v40, v40 row_shr:4 row_mask:0xf bank_mask:0xf bound_ctrl:1
	s_nop 1
	v_add_f32_dpp v121, v41, v41 row_shr:8 row_mask:0xf bank_mask:0xf bound_ctrl:1
	s_nop 0
	v_readlane_b32 s32, v121, 15
	ds_bpermute_b32 v96, v88, v121
	ds_bpermute_b32 v97, v89, v121
	ds_bpermute_b32 v98, v90, v121
	ds_bpermute_b32 v99, v91, v121
	ds_bpermute_b32 v104, v88, v122
	ds_bpermute_b32 v105, v89, v122
	ds_bpermute_b32 v106, v90, v122
	ds_bpermute_b32 v107, v91, v122
	v_exp_f32_e32 v120, s32
	s_waitcnt lgkmcnt(0)
	v_sub_f32_e32 v108, s32, v96
	v_mul_f32_e32 v104, v52, v104
	v_sub_f32_e32 v109, s32, v97
	v_mul_f32_e32 v105, v53, v105
	v_sub_f32_e32 v110, s32, v98
	v_mul_f32_e32 v106, v54, v106
	v_sub_f32_e32 v111, s32, v99
	v_mul_f32_e32 v107, v55, v107
	v_exp_f32_e32 v108, v108
	v_exp_f32_e32 v109, v109
	v_exp_f32_e32 v110, v110
	v_exp_f32_e32 v111, v111
	v_mul_f32_e32 v108, v104, v108
	v_mul_f32_e32 v109, v105, v109
	v_mul_f32_e32 v110, v106, v110
	v_mul_f32_e32 v111, v107, v111
	s_waitcnt vmcnt(56)
	v_mfma_f32_16x16x4_f32 v[36:39], v12, v28, 0
	v_mfma_f32_16x16x4_f32 v[44:47], v28, v72, 0
	global_load_short_d16_hi v28, v80, s[70:71] offset:512
	global_load_short_d16_hi v12, v80, s[70:71] offset:0
	s_waitcnt vmcnt(56)
	v_mfma_f32_16x16x4_f32 v[36:39], v13, v29, v[36:39]
	v_mfma_f32_16x16x4_f32 v[44:47], v29, v73, v[44:47]
	global_load_short_d16_hi v29, v80, s[70:71] offset:514
	global_load_short_d16_hi v13, v80, s[70:71] offset:2
	s_waitcnt vmcnt(56)
	v_mfma_f32_16x16x4_f32 v[36:39], v14, v30, v[36:39]
	v_mfma_f32_16x16x4_f32 v[44:47], v30, v74, v[44:47]
	global_load_short_d16_hi v30, v80, s[70:71] offset:516
	global_load_short_d16_hi v14, v80, s[70:71] offset:4
	s_waitcnt vmcnt(56)
	v_mfma_f32_16x16x4_f32 v[36:39], v15, v31, v[36:39]
	v_mfma_f32_16x16x4_f32 v[44:47], v31, v75, v[44:47]
	global_load_short_d16_hi v31, v80, s[70:71] offset:518
	global_load_short_d16_hi v15, v80, s[70:71] offset:6
	s_waitcnt vmcnt(56)
	v_mfma_f32_16x16x4_f32 v[36:39], v16, v32, v[36:39]
	v_mfma_f32_16x16x4_f32 v[44:47], v32, v76, v[44:47]
	global_load_short_d16_hi v32, v80, s[70:71] offset:544
	global_load_short_d16_hi v16, v80, s[70:71] offset:32
	s_waitcnt vmcnt(56)
	v_mfma_f32_16x16x4_f32 v[36:39], v17, v33, v[36:39]
	v_mfma_f32_16x16x4_f32 v[44:47], v33, v77, v[44:47]
	global_load_short_d16_hi v33, v80, s[70:71] offset:546
	global_load_short_d16_hi v17, v80, s[70:71] offset:34
	s_waitcnt vmcnt(56)
	v_mfma_f32_16x16x4_f32 v[36:39], v18, v34, v[36:39]
	v_mfma_f32_16x16x4_f32 v[44:47], v34, v78, v[44:47]
	global_load_short_d16_hi v34, v80, s[70:71] offset:548
	global_load_short_d16_hi v18, v80, s[70:71] offset:36
	s_waitcnt vmcnt(56)
	v_mfma_f32_16x16x4_f32 v[36:39], v19, v35, v[36:39]
	v_mfma_f32_16x16x4_f32 v[44:47], v35, v79, v[44:47]
	global_load_short_d16_hi v35, v80, s[70:71] offset:550
	global_load_short_d16_hi v19, v80, s[70:71] offset:38
	s_cmp_eq_u32 s77, 0
	s_cbranch_scc1 .Lssd1_w0_1
	s_nop 5
	ds_write_b128 v123, v[36:39] offset:8192
	ds_write_b128 v123, v[44:47] offset:12288
	s_waitcnt lgkmcnt(0)
	s_barrier
	s_branch .Lssd1_mrg_1
.Lssd1_w0_1:
	s_barrier
	ds_read_b128 v[128:131], v124 offset:9216
	ds_read_b128 v[132:135], v124 offset:13312
	ds_read_b128 v[136:139], v124 offset:10240
	ds_read_b128 v[140:143], v124 offset:14336
	ds_read_b128 v[144:147], v124 offset:11264
	ds_read_b128 v[150:153], v124 offset:15360
	s_waitcnt vmcnt(29)
	v_mul_f32_e32 v116, 0xbfb8aa3b, v56
	v_exp_f32_e32 v116, v116
	v_mul_f32_e32 v112, s27, v52
	v_sub_f32_e32 v100, v121, v96
	v_mul_f32_e32 v117, 0xbfb8aa3b, v57
	v_exp_f32_e32 v117, v117
	v_mul_f32_e32 v113, s27, v53
	v_sub_f32_e32 v101, v121, v97
	v_mul_f32_e32 v118, 0xbfb8aa3b, v58
	v_exp_f32_e32 v118, v118
	v_mul_f32_e32 v114, s27, v54
	v_sub_f32_e32 v102, v121, v98
	v_mul_f32_e32 v119, 0xbfb8aa3b, v59
	v_exp_f32_e32 v119, v119
	v_mul_f32_e32 v115, s27, v55
	v_sub_f32_e32 v103, v121, v99
	v_add_f32_e32 v116, 1.0, v116
	v_min_f32_e32 v100, 0, v100
	v_add_f32_e32 v117, 1.0, v117
	v_min_f32_e32 v101, 0, v101
	v_add_f32_e32 v118, 1.0, v118
	v_min_f32_e32 v102, 0, v102
	v_add_f32_e32 v119, 1.0, v119
	v_min_f32_e32 v103, 0, v103
	v_rcp_f32_e32 v116, v116
	v_add_f32_e32 v100, v92, v100
	v_rcp_f32_e32 v117, v117
	v_add_f32_e32 v101, v93, v101
	v_rcp_f32_e32 v118, v118
	v_add_f32_e32 v102, v94, v102
	v_rcp_f32_e32 v119, v119
	v_add_f32_e32 v103, v95, v103
	v_mul_f32_e32 v116, v116, v56
	v_exp_f32_e32 v100, v100
	v_exp_f32_e32 v96, v96
	v_mul_f32_e32 v117, v117, v57
	v_exp_f32_e32 v101, v101
	v_exp_f32_e32 v97, v97
	v_mul_f32_e32 v118, v118, v58
	v_exp_f32_e32 v102, v102
	v_exp_f32_e32 v98, v98
	v_mul_f32_e32 v119, v119, v59
	v_exp_f32_e32 v103, v103
	v_exp_f32_e32 v99, v99
	s_waitcnt lgkmcnt(0)
	v_add_f32_e32 v36, v36, v128
	v_add_f32_e32 v37, v37, v129
	v_add_f32_e32 v38, v38, v130
	v_add_f32_e32 v39, v39, v131
	v_add_f32_e32 v44, v44, v132
	v_add_f32_e32 v45, v45, v133
	v_add_f32_e32 v46, v46, v134
	v_add_f32_e32 v47, v47, v135
	v_add_f32_e32 v36, v36, v136
	v_add_f32_e32 v37, v37, v137
	v_add_f32_e32 v38, v38, v138
	v_add_f32_e32 v39, v39, v139
	v_add_f32_e32 v44, v44, v140
	v_add_f32_e32 v45, v45, v141
	v_add_f32_e32 v46, v46, v142
	v_add_f32_e32 v47, v47, v143
	v_add_f32_e32 v36, v36, v144
	v_add_f32_e32 v37, v37, v145
	v_add_f32_e32 v38, v38, v146
	v_add_f32_e32 v39, v39, v147
	v_add_f32_e32 v44, v44, v150
	v_add_f32_e32 v45, v45, v151
	v_add_f32_e32 v46, v46, v152
	v_add_f32_e32 v47, v47, v153
	v_mul_f32_e32 v36, v36, v100
	v_mul_f32_e32 v37, v37, v101
	v_mul_f32_e32 v38, v38, v102
	v_mul_f32_e32 v39, v39, v103
	v_mul_f32_e32 v44, v44, v96
	v_mul_f32_e32 v45, v45, v97
	v_mul_f32_e32 v46, v46, v98
	v_mul_f32_e32 v47, v47, v99
	s_nop 0
	s_nop 0
	v_mfma_f32_16x16x4_f32 v[44:47], v36, v104, v[44:47]
	v_mfma_f32_16x16x4_f32 v[44:47], v37, v105, v[44:47]
	v_mfma_f32_16x16x4_f32 v[44:47], v38, v106, v[44:47]
	v_mfma_f32_16x16x4_f32 v[44:47], v39, v107, v[44:47]
	global_load_dword v56, v86, s[74:75]
	global_load_short_d16_hi v56, v81, s[64:65]
	global_load_short_d16_hi v57, v82, s[64:65]
	global_load_short_d16_hi v58, v83, s[64:65]
	global_load_short_d16_hi v59, v84, s[64:65]
	s_nop 5
	v_add_f32_e32 v44, v44, v112
	v_add_f32_e32 v45, v45, v113
	v_add_f32_e32 v46, v46, v114
	v_add_f32_e32 v47, v47, v115
	v_mul_f32_e32 v44, v44, v116
	v_mul_f32_e32 v45, v45, v117
	v_mul_f32_e32 v46, v46, v118
	v_mul_f32_e32 v47, v47, v119
	v_cvt_pk_bf16_f32 v40, v44, v45
	v_cvt_pk_bf16_f32 v41, v46, v47
	global_store_short v81, v40, s[62:63]
	global_store_short_d16_hi v82, v40, s[62:63]
	global_store_short v83, v41, s[62:63]
	global_store_short_d16_hi v84, v41, s[62:63]
.Lssd1_mrg_1:
	s_nop 15
	global_load_short_d16_hi v52, v81, s[66:67] offset:3072
	global_load_short_d16_hi v53, v82, s[66:67] offset:3072
	global_load_short_d16_hi v54, v83, s[66:67] offset:3072
	global_load_short_d16_hi v55, v84, s[66:67] offset:3072
	global_load_dword v61, v85, s[72:73]
	v_mul_f32_e32 v72, v120, v72
	v_mul_f32_e32 v73, v120, v73
	v_mul_f32_e32 v74, v120, v74
	v_mul_f32_e32 v75, v120, v75
	v_mul_f32_e32 v76, v120, v76
	v_mul_f32_e32 v77, v120, v77
	v_mul_f32_e32 v78, v120, v78
	v_mul_f32_e32 v79, v120, v79
	s_waitcnt vmcnt(28)
	v_mfma_f32_16x16x4_f32 v[72:75], v64, v108, v[72:75]
	global_load_short_d16_hi v64, v81, s[68:69] offset:0
	s_waitcnt vmcnt(28)
	v_mfma_f32_16x16x4_f32 v[76:79], v65, v108, v[76:79]
	global_load_short_d16_hi v65, v81, s[68:69] offset:32
	s_waitcnt vmcnt(28)
	v_mfma_f32_16x16x4_f32 v[72:75], v66, v109, v[72:75]
	global_load_short_d16_hi v66, v82, s[68:69] offset:0
	s_waitcnt vmcnt(28)
	v_mfma_f32_16x16x4_f32 v[76:79], v67, v109, v[76:79]
	global_load_short_d16_hi v67, v82, s[68:69] offset:32
	s_waitcnt vmcnt(28)
	v_mfma_f32_16x16x4_f32 v[72:75], v68, v110, v[72:75]
	global_load_short_d16_hi v68, v83, s[68:69] offset:0
	s_waitcnt vmcnt(28)
	v_mfma_f32_16x16x4_f32 v[76:79], v69, v110, v[76:79]
	global_load_short_d16_hi v69, v83, s[68:69] offset:32
	s_waitcnt vmcnt(28)
	v_mfma_f32_16x16x4_f32 v[72:75], v70, v111, v[72:75]
	global_load_short_d16_hi v70, v84, s[68:69] offset:0
	s_waitcnt vmcnt(28)
	v_mfma_f32_16x16x4_f32 v[76:79], v71, v111, v[76:79]
	global_load_short_d16_hi v71, v84, s[68:69] offset:32
	s_add_i32 s57, s57, 1
	s_cmp_lt_i32 s57, s76
	s_cbranch_scc1 .Lssd1_loop
.Lssd1_fin:
	s_waitcnt vmcnt(0)
	s_nop 15
	s_lshl_b64 s[0:1], s[10:11], 3
	s_add_u32 s0, s0, s16
	s_addc_u32 s1, s1, s17
	s_add_u32 s0, s0, s26
	s_addc_u32 s1, s1, 0
	s_lshl_b64 s[0:1], s[0:1], 15
	s_add_u32 s0, s42, s0
	s_addc_u32 s1, s43, s1
	s_cmp_lt_i32 s54, 8
	s_mov_b32 s4, 0x8200000
	s_cselect_b32 s4, s4, 0x8c4c000
	s_add_u32 s0, s0, s4
	s_addc_u32 s1, s1, 0
	global_store_dwordx4 v87, v[72:75], s[0:1] offset:0
	global_store_dwordx4 v87, v[76:79], s[0:1] offset:64
	s_waitcnt vmcnt(0)
	v_mov_b32_e32 v20, v148
	v_readlane_b32 s55, v159, 52
	s_or_b32 s0, s26, s56
	s_cmp_eq_u32 s0, 0
	s_barrier
	s_cbranch_scc1 .LBB0_1075
	s_branch .LBB0_1019
